# K-loops P2/P6/P9/DFT: s_setprio 1 lines removed (A/B of priority raise that both SIMD partners shared)
# baseline (speedup 1.0000x reference)
; DI void wait_vm0() { asm volatile("s_waitcnt vmcnt(0)" ::: "memory"); }
; DI void bar_() { __builtin_amdgcn_s_barrier(); }
; #define GLDS(gp, lp) __builtin_amdgcn_global_load_lds((const unsigned*)(gp), (__attribute__((address_space(3))) unsigned*)(lp), 16, 0, 0)
; #define SB_ __builtin_amdgcn_sched_barrier(0)
; #define LOADF(A_, B_, ks) do { const int po_ = (((ks) * 2 + hh) ^ sw) * 16; \
;       _Pragma("unroll") for (int tm = 0; tm < TM; ++tm) A_[tm] = *(const bf16x8*)(As + tm * 32 * LDR + po_); \
;       _Pragma("unroll") for (int tn = 0; tn < TN; ++tn) B_[tn] = *(const bf16x8*)(Bs + tn * 32 * LDR + po_); } while (0)
; template <int TM, int TN, int WM, int WN, bool SUMSQ, int NST, class AF, class BF, class AFN, class BFN>
; DI void gemm8x(f32x16 (&acc)[TM][TN], AF arow, BF brow, int K, char* smem, float& sumsq, bool pre, bool hasNext, AFN arowN, BFN browN) {
;     ...
;   auto compute = [&](const char* cur, char* nxt, bool issue, const bf16_t* q0, const bf16_t* q1, const bf16_t* q2, const bf16_t* q3,
;                      const bf16_t* s0, const bf16_t* s1, const bf16_t* s2, const bf16_t* s3) {
;     const char* As = cur + aoff;
;     const char* Bs = cur + boff;
;     char* l_ = nxt + t * 16; char* m_ = l_ + RA * LDR;
;     bf16x8 a0[TM], b0[TN], a1[TM], b1[TN];
;     ...
;     LOADF(a0, b0, 0);
;     LOADF(a1, b1, 1);
;     SB_;
;     if (issue) { if (a0v) GLDS(q0, l_); if (a1v) GLDS(q1, l_ + 8192); }
;     SB_;
;     __builtin_amdgcn_s_setprio(1);
;     MMF(a0, b0);
;     LOADF(a0, b0, 2);
;     SB_;
;     if (issue) { if (a2v) GLDS(q2, l_ + 16384); if (a3v) GLDS(q3, l_ + 24576); }
;     SB_;
;     MMF(a1, b1);
;     LOADF(a1, b1, 3);
;     SB_;
;     if (issue) { if (b0v) GLDS(s0, m_); if (b1v) GLDS(s1, m_ + 8192); }
;     SB_;
;     MMF(a0, b0);
;     SB_;
;     if (issue) { if (b2v) GLDS(s2, m_ + 16384); if (b3v) GLDS(s3, m_ + 24576); }
;     SB_;
;     MMF(a1, b1);
;     __builtin_amdgcn_s_setprio(0);
;     ...
;   for (int kt = 0; kt < nk - 1; ++kt) {
;     SB_;
;     if (NST == 2) {
;       const int ko = (kt + 1) * 64;
;       compute(smem + (kt & 1) * STAGE, smem + ((kt + 1) & 1) * STAGE, true, pa0 + ko, pa1 + ko, pa2 + ko, pa3 + ko, pb0 + ko, pb1 + ko, pb2 + ko, pb3 + ko);
;       SB_;
;       wait_vm0(); bar_();
.Lp2_loop:
	s_and_b32 s37, s13, 0x10000
	v_add_u32_e32 v225, s37, v222
	v_add_u32_e32 v224, s37, v217
	s_xor_b32 s37, s37, 0x10000
	s_add_i32 s37, s37, s66
	v_add_u32_e32 v226, v225, v216
	v_add_u32_e32 v227, v224, v216
	v_mfma_f32_32x32x16_bf16 v[112:127], v[148:151], v[140:143], v[112:127]
	ds_read_b128 v[164:167], v226 offset:32768
	ds_read_b128 v[172:175], v227
	s_mov_b32 m0, s37
	v_lshl_add_u64 v[228:229], v[196:197], 0, s[44:45]
	global_load_lds_dwordx4 v[228:229], off
	v_mfma_f32_32x32x16_bf16 v[48:63], v[148:151], v[132:135], v[48:63]
	ds_read_b128 v[156:159], v226 offset:36864
	ds_read_b128 v[168:171], v227 offset:4096
	s_add_u32 m0, s37, 0x2000
	v_lshl_add_u64 v[230:231], v[198:199], 0, s[44:45]
	global_load_lds_dwordx4 v[230:231], off
	v_mfma_f32_32x32x16_bf16 v[96:111], v[144:147], v[140:143], v[96:111]
	ds_read_b128 v[160:163], v227 offset:8192
	s_add_u32 m0, s37, 0x4000
	v_lshl_add_u64 v[228:229], v[200:201], 0, s[44:45]
	global_load_lds_dwordx4 v[228:229], off
	v_mfma_f32_32x32x16_bf16 v[32:47], v[144:147], v[132:135], v[32:47]
	ds_read_b128 v[152:155], v227 offset:12288
	s_add_u32 m0, s37, 0x6000
	v_lshl_add_u64 v[230:231], v[202:203], 0, s[44:45]
	global_load_lds_dwordx4 v[230:231], off
	v_mfma_f32_32x32x16_bf16 v[80:95], v[136:139], v[140:143], v[80:95]
	s_add_u32 m0, s37, 0x8000
	v_lshl_add_u64 v[228:229], v[204:205], 0, s[44:45]
	global_load_lds_dwordx4 v[228:229], off
	v_mfma_f32_32x32x16_bf16 v[16:31], v[136:139], v[132:135], v[16:31]
	s_add_u32 m0, s37, 0xa000
	v_lshl_add_u64 v[230:231], v[206:207], 0, s[44:45]
	global_load_lds_dwordx4 v[230:231], off
	v_mfma_f32_32x32x16_bf16 v[64:79], v[128:131], v[140:143], v[64:79]
	s_add_u32 m0, s37, 0xc000
	v_lshl_add_u64 v[228:229], v[208:209], 0, s[44:45]
	global_load_lds_dwordx4 v[228:229], off
	v_mfma_f32_32x32x16_bf16 v[0:15], v[128:131], v[132:135], v[0:15]
	s_add_u32 m0, s37, 0xe000
	v_lshl_add_u64 v[230:231], v[210:211], 0, s[44:45]
	global_load_lds_dwordx4 v[230:231], off
.Lp2_g0:
	v_add_u32_e32 v226, v225, v215
	v_add_u32_e32 v227, v224, v215
	s_waitcnt lgkmcnt(0)
	v_mfma_f32_32x32x16_bf16 v[112:127], v[172:175], v[164:167], v[112:127]
	ds_read_b128 v[140:143], v226 offset:32768
	ds_read_b128 v[148:151], v227
	v_mfma_f32_32x32x16_bf16 v[48:63], v[172:175], v[156:159], v[48:63]
	ds_read_b128 v[132:135], v226 offset:36864
	ds_read_b128 v[144:147], v227 offset:4096
	v_mfma_f32_32x32x16_bf16 v[96:111], v[168:171], v[164:167], v[96:111]
	ds_read_b128 v[136:139], v227 offset:8192
	v_mfma_f32_32x32x16_bf16 v[32:47], v[168:171], v[156:159], v[32:47]
	ds_read_b128 v[128:131], v227 offset:12288
	v_mfma_f32_32x32x16_bf16 v[80:95], v[160:163], v[164:167], v[80:95]
	v_mfma_f32_32x32x16_bf16 v[16:31], v[160:163], v[156:159], v[16:31]
	v_mfma_f32_32x32x16_bf16 v[64:79], v[152:155], v[164:167], v[64:79]
	v_mfma_f32_32x32x16_bf16 v[0:15], v[152:155], v[156:159], v[0:15]
	v_add_u32_e32 v226, v225, v214
	v_add_u32_e32 v227, v224, v214
	s_waitcnt lgkmcnt(0)
	v_mfma_f32_32x32x16_bf16 v[112:127], v[148:151], v[140:143], v[112:127]
	ds_read_b128 v[164:167], v226 offset:32768
	ds_read_b128 v[172:175], v227
	v_mfma_f32_32x32x16_bf16 v[48:63], v[148:151], v[132:135], v[48:63]
	ds_read_b128 v[156:159], v226 offset:36864
	ds_read_b128 v[168:171], v227 offset:4096
	v_mfma_f32_32x32x16_bf16 v[96:111], v[144:147], v[140:143], v[96:111]
	ds_read_b128 v[160:163], v227 offset:8192
	v_mfma_f32_32x32x16_bf16 v[32:47], v[144:147], v[132:135], v[32:47]
	ds_read_b128 v[152:155], v227 offset:12288
	v_mfma_f32_32x32x16_bf16 v[80:95], v[136:139], v[140:143], v[80:95]
	v_mfma_f32_32x32x16_bf16 v[16:31], v[136:139], v[132:135], v[16:31]
	v_mfma_f32_32x32x16_bf16 v[64:79], v[128:131], v[140:143], v[64:79]
	v_mfma_f32_32x32x16_bf16 v[0:15], v[128:131], v[132:135], v[0:15]
	v_add_u32_e32 v226, v225, v213
	v_add_u32_e32 v227, v224, v213
	s_waitcnt lgkmcnt(0)
	v_mfma_f32_32x32x16_bf16 v[112:127], v[172:175], v[164:167], v[112:127]
	ds_read_b128 v[140:143], v226 offset:32768
	ds_read_b128 v[148:151], v227
	v_mfma_f32_32x32x16_bf16 v[48:63], v[172:175], v[156:159], v[48:63]
	ds_read_b128 v[132:135], v226 offset:36864
	ds_read_b128 v[144:147], v227 offset:4096
	v_mfma_f32_32x32x16_bf16 v[96:111], v[168:171], v[164:167], v[96:111]
	ds_read_b128 v[136:139], v227 offset:8192
	v_mfma_f32_32x32x16_bf16 v[32:47], v[168:171], v[156:159], v[32:47]
	ds_read_b128 v[128:131], v227 offset:12288
	v_mfma_f32_32x32x16_bf16 v[80:95], v[160:163], v[164:167], v[80:95]
	v_mfma_f32_32x32x16_bf16 v[16:31], v[160:163], v[156:159], v[16:31]
	v_mfma_f32_32x32x16_bf16 v[64:79], v[152:155], v[164:167], v[64:79]
	v_mfma_f32_32x32x16_bf16 v[0:15], v[152:155], v[156:159], v[0:15]
	s_setprio 0
	s_waitcnt vmcnt(0) lgkmcnt(0)
	s_add_i32 s13, s13, 0x10000
	s_add_u32 s44, s44, 0x80
	s_addc_u32 s45, s45, 0
	s_cmpk_eq_i32 s44, 0x780
	s_barrier
	s_cbranch_scc0 .Lp2_loop
; #define GLDS(gp, lp) __builtin_amdgcn_global_load_lds((const unsigned*)(gp), (__attribute__((address_space(3))) unsigned*)(lp), 16, 0, 0)
; #define SB_ __builtin_amdgcn_sched_barrier(0)
; #define LOADF(A_, B_, ks) do { const int po_ = (((ks) * 2 + hh) ^ sw) * 16; \
;       _Pragma("unroll") for (int tm = 0; tm < TM; ++tm) A_[tm] = *(const bf16x8*)(As + tm * 32 * LDR + po_); \
;       _Pragma("unroll") for (int tn = 0; tn < TN; ++tn) B_[tn] = *(const bf16x8*)(Bs + tn * 32 * LDR + po_); } while (0)
; template <int TM, int TN, int WM, int WN, bool SUMSQ, int NST, class AF, class BF, class AFN, class BFN>
; DI void gemm8x(f32x16 (&acc)[TM][TN], AF arow, BF brow, int K, char* smem, float& sumsq, bool pre, bool hasNext, AFN arowN, BFN browN) {
;     ...
;   auto compute = [&](const char* cur, char* nxt, bool issue, const bf16_t* q0, const bf16_t* q1, const bf16_t* q2, const bf16_t* q3,
;                      const bf16_t* s0, const bf16_t* s1, const bf16_t* s2, const bf16_t* s3) {
;     const char* As = cur + aoff;
;     const char* Bs = cur + boff;
;     char* l_ = nxt + t * 16; char* m_ = l_ + RA * LDR;
;     bf16x8 a0[TM], b0[TN], a1[TM], b1[TN];
;     ...
;     LOADF(a0, b0, 0);
;     LOADF(a1, b1, 1);
;     SB_;
;     if (issue) { if (a0v) GLDS(q0, l_); if (a1v) GLDS(q1, l_ + 8192); }
;     SB_;
;     __builtin_amdgcn_s_setprio(1);
;     MMF(a0, b0);
;     LOADF(a0, b0, 2);
;     SB_;
;     if (issue) { if (a2v) GLDS(q2, l_ + 16384); if (a3v) GLDS(q3, l_ + 24576); }
;     SB_;
;     MMF(a1, b1);
;     LOADF(a1, b1, 3);
;     SB_;
;     if (issue) { if (b0v) GLDS(s0, m_); if (b1v) GLDS(s1, m_ + 8192); }
;     SB_;
;     MMF(a0, b0);
;     SB_;
;     if (issue) { if (b2v) GLDS(s2, m_ + 16384); if (b3v) GLDS(s3, m_ + 24576); }
;     SB_;
;     MMF(a1, b1);
;     __builtin_amdgcn_s_setprio(0);
;     ...
;     const bf16_t *q0 = pa0, *q1 = pa0, *q2 = pa0, *q3 = pa0, *s0 = pa0, *s1 = pa0, *s2 = pa0, *s3 = pa0;
;     if (hasNext) {
;       q0 = arowN(a0v ? row0 : 0) + c * 8; q1 = arowN(a1v ? row0 + 64 : 0) + c * 8; q2 = arowN(a2v ? row0 + 128 : 0) + c * 8; q3 = arowN(a3v ? row0 + 192 : 0) + c * 8;
;       s0 = browN(b0v ? row0 : 0) + c * 8; s1 = browN(b1v ? row0 + 64 : 0) + c * 8; s2 = browN(b2v ? row0 + 128 : 0) + c * 8; s3 = browN(b3v ? row0 + 192 : 0) + c * 8;
;     }
;     SB_;
;     compute(smem + ((nk - 1) & 1) * STAGE, smem, hasNext, q0, q1, q2, q3, s0, s1, s2, s3);
	s_and_b32 s37, s13, 0x10000
	v_add_u32_e32 v225, s37, v222
	v_add_u32_e32 v224, s37, v217
	s_xor_b32 s37, s37, 0x10000
	s_add_i32 s37, s37, s66
	v_add_u32_e32 v226, v225, v216
	v_add_u32_e32 v227, v224, v216
	v_mfma_f32_32x32x16_bf16 v[112:127], v[148:151], v[140:143], v[112:127]
	ds_read_b128 v[164:167], v226 offset:32768
	ds_read_b128 v[172:175], v227
	v_mfma_f32_32x32x16_bf16 v[48:63], v[148:151], v[132:135], v[48:63]
	ds_read_b128 v[156:159], v226 offset:36864
	ds_read_b128 v[168:171], v227 offset:4096
	v_mfma_f32_32x32x16_bf16 v[96:111], v[144:147], v[140:143], v[96:111]
	ds_read_b128 v[160:163], v227 offset:8192
	v_mfma_f32_32x32x16_bf16 v[32:47], v[144:147], v[132:135], v[32:47]
	ds_read_b128 v[152:155], v227 offset:12288
	v_mfma_f32_32x32x16_bf16 v[80:95], v[136:139], v[140:143], v[80:95]
	v_mfma_f32_32x32x16_bf16 v[16:31], v[136:139], v[132:135], v[16:31]
	v_mfma_f32_32x32x16_bf16 v[64:79], v[128:131], v[140:143], v[64:79]
	v_mfma_f32_32x32x16_bf16 v[0:15], v[128:131], v[132:135], v[0:15]
	v_add_u32_e32 v226, v225, v215
	v_add_u32_e32 v227, v224, v215
	s_waitcnt lgkmcnt(0)
	v_mfma_f32_32x32x16_bf16 v[112:127], v[172:175], v[164:167], v[112:127]
	ds_read_b128 v[140:143], v226 offset:32768
	ds_read_b128 v[148:151], v227
	v_mfma_f32_32x32x16_bf16 v[48:63], v[172:175], v[156:159], v[48:63]
	ds_read_b128 v[132:135], v226 offset:36864
	ds_read_b128 v[144:147], v227 offset:4096
	v_mfma_f32_32x32x16_bf16 v[96:111], v[168:171], v[164:167], v[96:111]
	ds_read_b128 v[136:139], v227 offset:8192
	v_mfma_f32_32x32x16_bf16 v[32:47], v[168:171], v[156:159], v[32:47]
	ds_read_b128 v[128:131], v227 offset:12288
	v_mfma_f32_32x32x16_bf16 v[80:95], v[160:163], v[164:167], v[80:95]
	v_mfma_f32_32x32x16_bf16 v[16:31], v[160:163], v[156:159], v[16:31]
	v_mfma_f32_32x32x16_bf16 v[64:79], v[152:155], v[164:167], v[64:79]
	v_mfma_f32_32x32x16_bf16 v[0:15], v[152:155], v[156:159], v[0:15]
	v_add_u32_e32 v226, v225, v214
	v_add_u32_e32 v227, v224, v214
	s_waitcnt lgkmcnt(0)
	v_mfma_f32_32x32x16_bf16 v[112:127], v[148:151], v[140:143], v[112:127]
	ds_read_b128 v[164:167], v226 offset:32768
	ds_read_b128 v[172:175], v227
	v_mfma_f32_32x32x16_bf16 v[48:63], v[148:151], v[132:135], v[48:63]
	ds_read_b128 v[156:159], v226 offset:36864
	ds_read_b128 v[168:171], v227 offset:4096
	v_mfma_f32_32x32x16_bf16 v[96:111], v[144:147], v[140:143], v[96:111]
	ds_read_b128 v[160:163], v227 offset:8192
	v_mfma_f32_32x32x16_bf16 v[32:47], v[144:147], v[132:135], v[32:47]
	ds_read_b128 v[152:155], v227 offset:12288
	v_mfma_f32_32x32x16_bf16 v[80:95], v[136:139], v[140:143], v[80:95]
	v_mfma_f32_32x32x16_bf16 v[16:31], v[136:139], v[132:135], v[16:31]
	v_mfma_f32_32x32x16_bf16 v[64:79], v[128:131], v[140:143], v[64:79]
	v_mfma_f32_32x32x16_bf16 v[0:15], v[128:131], v[132:135], v[0:15]
	v_add_u32_e32 v226, v225, v213
	v_add_u32_e32 v227, v224, v213
	s_waitcnt lgkmcnt(0)
	v_mfma_f32_32x32x16_bf16 v[112:127], v[172:175], v[164:167], v[112:127]
	ds_read_b128 v[140:143], v226 offset:32768
	ds_read_b128 v[148:151], v227
	v_mfma_f32_32x32x16_bf16 v[48:63], v[172:175], v[156:159], v[48:63]
	ds_read_b128 v[132:135], v226 offset:36864
	ds_read_b128 v[144:147], v227 offset:4096
	v_mfma_f32_32x32x16_bf16 v[96:111], v[168:171], v[164:167], v[96:111]
	ds_read_b128 v[136:139], v227 offset:8192
	v_mfma_f32_32x32x16_bf16 v[32:47], v[168:171], v[156:159], v[32:47]
	ds_read_b128 v[128:131], v227 offset:12288
	v_mfma_f32_32x32x16_bf16 v[80:95], v[160:163], v[164:167], v[80:95]
	v_mfma_f32_32x32x16_bf16 v[16:31], v[160:163], v[156:159], v[16:31]
	v_mfma_f32_32x32x16_bf16 v[64:79], v[152:155], v[164:167], v[64:79]
	v_mfma_f32_32x32x16_bf16 v[0:15], v[152:155], v[156:159], v[0:15]
	s_and_b64 vcc, exec, s[40:41]
	s_cbranch_vccz .Lp2_nonext
	s_mov_b32 s43, s31
	s_lshl_b64 s[42:43], s[42:43], 19
	s_add_u32 s42, s14, s42
	s_addc_u32 s43, s15, s43
	s_mov_b32 s13, s31
	v_lshl_add_u64 v[226:227], s[42:43], 0, v[188:189]
	s_lshl_b64 s[12:13], s[12:13], 19
	v_lshl_add_u64 v[186:187], v[226:227], 0, v[184:185]
	v_lshl_add_u64 v[226:227], s[42:43], 0, v[190:191]
	s_add_u32 s12, s16, s12
	v_lshl_add_u64 v[164:165], v[226:227], 0, v[184:185]
	v_lshl_add_u64 v[226:227], s[42:43], 0, v[192:193]
	s_addc_u32 s13, s17, s13
	v_lshl_add_u64 v[206:207], v[226:227], 0, v[184:185]
	v_lshl_add_u64 v[226:227], s[42:43], 0, v[194:195]
	v_lshl_add_u64 v[204:205], v[226:227], 0, v[184:185]
	v_lshl_add_u64 v[226:227], s[12:13], 0, v[188:189]
	v_lshl_add_u64 v[202:203], v[226:227], 0, v[184:185]
	v_lshl_add_u64 v[226:227], s[12:13], 0, v[190:191]
	v_lshl_add_u64 v[200:201], v[226:227], 0, v[184:185]
	v_lshl_add_u64 v[226:227], s[12:13], 0, v[192:193]
	v_lshl_add_u64 v[198:199], v[226:227], 0, v[184:185]
	v_lshl_add_u64 v[226:227], s[12:13], 0, v[194:195]
	v_lshl_add_u64 v[196:197], v[226:227], 0, v[184:185]
	s_mov_b32 m0, s66
	s_nop 0
	global_load_lds_dwordx4 v[186:187], off
	s_add_u32 m0, s66, 0x2000
	s_nop 0
	global_load_lds_dwordx4 v[164:165], off
	s_add_u32 m0, s66, 0x4000
	s_nop 0
	global_load_lds_dwordx4 v[206:207], off
	s_add_u32 m0, s66, 0x6000
	s_nop 0
	global_load_lds_dwordx4 v[204:205], off
	s_add_u32 m0, s66, 0x8000
	s_nop 0
	global_load_lds_dwordx4 v[202:203], off
	s_add_u32 m0, s66, 0xa000
	s_nop 0
	global_load_lds_dwordx4 v[200:201], off
	s_add_u32 m0, s66, 0xc000
	s_nop 0
	global_load_lds_dwordx4 v[198:199], off
	s_add_u32 m0, s66, 0xe000
	s_nop 0
	global_load_lds_dwordx4 v[196:197], off

; DI void wait_vm0() { asm volatile("s_waitcnt vmcnt(0)" ::: "memory"); }
; DI void bar_() { __builtin_amdgcn_s_barrier(); }
; #define GLDS(gp, lp) __builtin_amdgcn_global_load_lds((const unsigned*)(gp), (__attribute__((address_space(3))) unsigned*)(lp), 16, 0, 0)
; #define SB_ __builtin_amdgcn_sched_barrier(0)
; template <int TM, int TN, int WM, int WN, bool SUMSQ, int NST, class AF, class BF, class AFN, class BFN>
; DI void gemm8x(f32x16 (&acc)[TM][TN], AF arow, BF brow, int K, char* smem, float& sumsq, bool pre, bool hasNext, AFN arowN, BFN browN) {
;     ...
;   auto compute = [&](const char* cur, char* nxt, bool issue, const bf16_t* q0, const bf16_t* q1, const bf16_t* q2, const bf16_t* q3,
;                      const bf16_t* s0, const bf16_t* s1, const bf16_t* s2, const bf16_t* s3) {
;     const char* As = cur + aoff;
;     const char* Bs = cur + boff;
;     char* l_ = nxt + t * 16; char* m_ = l_ + RA * LDR;
;     bf16x8 a0[TM], b0[TN], a1[TM], b1[TN];
;     ...
;     LOADF(a0, b0, 0);
;     LOADF(a1, b1, 1);
;     SB_;
;     if (issue) { if (a0v) GLDS(q0, l_); if (a1v) GLDS(q1, l_ + 8192); }
;     SB_;
;     __builtin_amdgcn_s_setprio(1);
;     MMF(a0, b0);
;     LOADF(a0, b0, 2);
;     SB_;
;     if (issue) { if (a2v) GLDS(q2, l_ + 16384); if (a3v) GLDS(q3, l_ + 24576); }
;     SB_;
;     MMF(a1, b1);
;     LOADF(a1, b1, 3);
;     SB_;
;     if (issue) { if (b0v) GLDS(s0, m_); if (b1v) GLDS(s1, m_ + 8192); }
;     SB_;
;     MMF(a0, b0);
;     SB_;
;     if (issue) { if (b2v) GLDS(s2, m_ + 16384); if (b3v) GLDS(s3, m_ + 24576); }
;     SB_;
;     MMF(a1, b1);
;     __builtin_amdgcn_s_setprio(0);
;     ...
;     } else {
;       const int ko = (kt + 2) * 64; const bool iss = kt + 2 < nk;
;       const int sn = (sc_ == 0) ? 2 : sc_ - 1;
;       compute(smem + sc_ * STAGE, smem + sn * STAGE, iss, pa0 + ko, pa1 + ko, pa2 + ko, pa3 + ko, pb0 + ko, pb1 + ko, pb2 + ko, pb3 + ko);
;       SB_;
;       if (iss) asm volatile("s_waitcnt vmcnt(6)" ::: "memory"); else wait_vm0();
;       bar_();
;       sc_ = (sc_ == 2) ? 0 : sc_ + 1;
;     }
;   }
;   if (NST == 3) {
;     SB_;
;     compute(smem + sc_ * STAGE, smem, false, pa0, pa0, pa0, pa0, pa0, pa0, pa0, pa0);
.Ld1_loop:
	s_mul_i32 s99, s93, 0xc000
	v_add_u32_e32 v123, s99, v118
	v_add_u32_e32 v122, s99, v117
	s_add_i32 s99, s99, 0xffff4000
	s_cmp_lg_u32 s93, 0
	s_cselect_b32 s99, s99, 0x18000
	s_add_i32 s99, s99, s98
	v_add_u32_e32 v131, v123, v116
	v_add_u32_e32 v130, v122, v116
	v_mfma_f32_32x32x16_bf16 v[48:63], v[68:71], v[72:75], v[48:63]
	ds_read_b128 v[88:91], v131 offset:32768
	ds_read_b128 v[84:87], v130
	s_mov_b32 m0, s99
	v_lshl_add_u64 v[124:125], v[96:97], 0, s[54:55]
	global_load_lds_dwordx4 v[124:125], off
	v_mfma_f32_32x32x16_bf16 v[32:47], v[68:71], v[76:79], v[32:47]
	ds_read_b128 v[92:95], v131 offset:36864
	ds_read_b128 v[80:83], v130 offset:4096
	s_add_u32 m0, s99, 0x2000
	v_lshl_add_u64 v[126:127], v[110:111], 0, s[54:55]
	global_load_lds_dwordx4 v[126:127], off
	v_mfma_f32_32x32x16_bf16 v[16:31], v[64:67], v[72:75], v[16:31]
	s_add_u32 m0, s99, 0x4000
	v_lshl_add_u64 v[124:125], v[108:109], 0, s[54:55]
	global_load_lds_dwordx4 v[124:125], off
	s_add_u32 m0, s99, 0x6000
	v_lshl_add_u64 v[126:127], v[106:107], 0, s[54:55]
	global_load_lds_dwordx4 v[126:127], off
	v_mfma_f32_32x32x16_bf16 v[0:15], v[64:67], v[76:79], v[0:15]
	s_add_u32 m0, s99, 0x8000
	v_lshl_add_u64 v[124:125], v[104:105], 0, s[54:55]
	global_load_lds_dwordx4 v[124:125], off
	s_add_u32 m0, s99, 0xa000
	v_lshl_add_u64 v[126:127], v[102:103], 0, s[54:55]
	global_load_lds_dwordx4 v[126:127], off
.Ld1_g0:
	v_add_u32_e32 v131, v123, v115
	v_add_u32_e32 v130, v122, v115
	s_waitcnt lgkmcnt(0)
	v_mfma_f32_32x32x16_bf16 v[48:63], v[84:87], v[88:91], v[48:63]
	ds_read_b128 v[72:75], v131 offset:32768
	ds_read_b128 v[68:71], v130
	v_mfma_f32_32x32x16_bf16 v[32:47], v[84:87], v[92:95], v[32:47]
	ds_read_b128 v[76:79], v131 offset:36864
	ds_read_b128 v[64:67], v130 offset:4096
	v_mfma_f32_32x32x16_bf16 v[16:31], v[80:83], v[88:91], v[16:31]
	v_mfma_f32_32x32x16_bf16 v[0:15], v[80:83], v[92:95], v[0:15]
	v_add_u32_e32 v131, v123, v114
	v_add_u32_e32 v130, v122, v114
	s_waitcnt lgkmcnt(0)
	v_mfma_f32_32x32x16_bf16 v[48:63], v[68:71], v[72:75], v[48:63]
	ds_read_b128 v[88:91], v131 offset:32768
	ds_read_b128 v[84:87], v130
	v_mfma_f32_32x32x16_bf16 v[32:47], v[68:71], v[76:79], v[32:47]
	ds_read_b128 v[92:95], v131 offset:36864
	ds_read_b128 v[80:83], v130 offset:4096
	v_mfma_f32_32x32x16_bf16 v[16:31], v[64:67], v[72:75], v[16:31]
	v_mfma_f32_32x32x16_bf16 v[0:15], v[64:67], v[76:79], v[0:15]
	v_add_u32_e32 v131, v123, v113
	v_add_u32_e32 v130, v122, v113
	s_waitcnt lgkmcnt(0)
	v_mfma_f32_32x32x16_bf16 v[48:63], v[84:87], v[88:91], v[48:63]
	ds_read_b128 v[72:75], v131 offset:32768
	ds_read_b128 v[68:71], v130
	v_mfma_f32_32x32x16_bf16 v[32:47], v[84:87], v[92:95], v[32:47]
	ds_read_b128 v[76:79], v131 offset:36864
	ds_read_b128 v[64:67], v130 offset:4096
	v_mfma_f32_32x32x16_bf16 v[16:31], v[80:83], v[88:91], v[16:31]
	v_mfma_f32_32x32x16_bf16 v[0:15], v[80:83], v[92:95], v[0:15]
	s_setprio 0
	s_waitcnt vmcnt(6) lgkmcnt(0)
	s_add_i32 s100, s93, 1
	s_cmp_lg_u32 s93, 2
	s_cselect_b32 s93, s100, 0
	s_add_u32 s54, s54, 0x80
	s_addc_u32 s55, s55, 0
	s_cmpk_lg_i32 s54, 0xf00
	s_barrier
	s_cbranch_scc1 .Ld1_loop
	v_mfma_f32_32x32x16_bf16 v[48:63], v[68:71], v[72:75], v[48:63]
	v_mfma_f32_32x32x16_bf16 v[32:47], v[68:71], v[76:79], v[32:47]
	v_mfma_f32_32x32x16_bf16 v[16:31], v[64:67], v[72:75], v[16:31]
	v_mfma_f32_32x32x16_bf16 v[0:15], v[64:67], v[76:79], v[0:15]

; DI void wait_vm0() { asm volatile("s_waitcnt vmcnt(0)" ::: "memory"); }
; DI void bar_() { __builtin_amdgcn_s_barrier(); }
; #define GLDS(gp, lp) __builtin_amdgcn_global_load_lds((const unsigned*)(gp), (__attribute__((address_space(3))) unsigned*)(lp), 16, 0, 0)
; #define SB_ __builtin_amdgcn_sched_barrier(0)
; template <int TM, int TN, int WM, int WN, bool SUMSQ, int NST, class AF, class BF, class AFN, class BFN>
; DI void gemm8x(f32x16 (&acc)[TM][TN], AF arow, BF brow, int K, char* smem, float& sumsq, bool pre, bool hasNext, AFN arowN, BFN browN) {
;     ...
;   auto compute = [&](const char* cur, char* nxt, bool issue, const bf16_t* q0, const bf16_t* q1, const bf16_t* q2, const bf16_t* q3,
;                      const bf16_t* s0, const bf16_t* s1, const bf16_t* s2, const bf16_t* s3) {
;     const char* As = cur + aoff;
;     const char* Bs = cur + boff;
;     char* l_ = nxt + t * 16; char* m_ = l_ + RA * LDR;
;     bf16x8 a0[TM], b0[TN], a1[TM], b1[TN];
;     ...
;     LOADF(a0, b0, 0);
;     LOADF(a1, b1, 1);
;     SB_;
;     if (issue) { if (a0v) GLDS(q0, l_); if (a1v) GLDS(q1, l_ + 8192); }
;     SB_;
;     __builtin_amdgcn_s_setprio(1);
;     MMF(a0, b0);
;     LOADF(a0, b0, 2);
;     SB_;
;     if (issue) { if (a2v) GLDS(q2, l_ + 16384); if (a3v) GLDS(q3, l_ + 24576); }
;     SB_;
;     MMF(a1, b1);
;     LOADF(a1, b1, 3);
;     SB_;
;     if (issue) { if (b0v) GLDS(s0, m_); if (b1v) GLDS(s1, m_ + 8192); }
;     SB_;
;     MMF(a0, b0);
;     SB_;
;     if (issue) { if (b2v) GLDS(s2, m_ + 16384); if (b3v) GLDS(s3, m_ + 24576); }
;     SB_;
;     MMF(a1, b1);
;     __builtin_amdgcn_s_setprio(0);
;     ...
;     } else {
;       const int ko = (kt + 2) * 64; const bool iss = kt + 2 < nk;
;       const int sn = (sc_ == 0) ? 2 : sc_ - 1;
;       compute(smem + sc_ * STAGE, smem + sn * STAGE, iss, pa0 + ko, pa1 + ko, pa2 + ko, pa3 + ko, pb0 + ko, pb1 + ko, pb2 + ko, pb3 + ko);
;       SB_;
;       if (iss) asm volatile("s_waitcnt vmcnt(6)" ::: "memory"); else wait_vm0();
;       bar_();
;       sc_ = (sc_ == 2) ? 0 : sc_ + 1;
;     }
;   }
;   if (NST == 3) {
;     SB_;
;     compute(smem + sc_ * STAGE, smem, false, pa0, pa0, pa0, pa0, pa0, pa0, pa0, pa0);
.Ld2_loop:
	s_mul_i32 s99, s42, 0xc000
	v_add_u32_e32 v167, s99, v192
	v_add_u32_e32 v166, s99, v191
	s_add_i32 s99, s99, 0xffff4000
	s_cmp_lg_u32 s42, 0
	s_cselect_b32 s99, s99, 0x18000
	s_add_i32 s99, s99, s98
	v_add_u32_e32 v165, v167, v190
	v_add_u32_e32 v164, v166, v190
	v_mfma_f32_32x32x16_bf16 v[112:127], v[144:147], v[152:155], v[112:127]
	ds_read_b128 v[136:139], v165 offset:32768
	ds_read_b128 v[128:131], v164
	s_mov_b32 m0, s99
	v_lshl_add_u64 v[160:161], v[170:171], 0, s[48:49]
	global_load_lds_dwordx4 v[160:161], off
	v_mfma_f32_32x32x16_bf16 v[96:111], v[144:147], v[156:159], v[96:111]
	ds_read_b128 v[140:143], v165 offset:36864
	ds_read_b128 v[132:135], v164 offset:4096
	s_add_u32 m0, s99, 0x2000
	v_lshl_add_u64 v[162:163], v[184:185], 0, s[48:49]
	global_load_lds_dwordx4 v[162:163], off
	v_mfma_f32_32x32x16_bf16 v[80:95], v[148:151], v[152:155], v[80:95]
	s_add_u32 m0, s99, 0x4000
	v_lshl_add_u64 v[160:161], v[182:183], 0, s[48:49]
	global_load_lds_dwordx4 v[160:161], off
	s_add_u32 m0, s99, 0x6000
	v_lshl_add_u64 v[162:163], v[180:181], 0, s[48:49]
	global_load_lds_dwordx4 v[162:163], off
	v_mfma_f32_32x32x16_bf16 v[64:79], v[148:151], v[156:159], v[64:79]
	s_add_u32 m0, s99, 0x8000
	v_lshl_add_u64 v[160:161], v[178:179], 0, s[48:49]
	global_load_lds_dwordx4 v[160:161], off
	s_add_u32 m0, s99, 0xa000
	v_lshl_add_u64 v[162:163], v[176:177], 0, s[48:49]
	global_load_lds_dwordx4 v[162:163], off
.Ld2_g0:
	v_add_u32_e32 v165, v167, v189
	v_add_u32_e32 v164, v166, v189
	s_waitcnt lgkmcnt(0)
	v_mfma_f32_32x32x16_bf16 v[112:127], v[128:131], v[136:139], v[112:127]
	ds_read_b128 v[152:155], v165 offset:32768
	ds_read_b128 v[144:147], v164
	v_mfma_f32_32x32x16_bf16 v[96:111], v[128:131], v[140:143], v[96:111]
	ds_read_b128 v[156:159], v165 offset:36864
	ds_read_b128 v[148:151], v164 offset:4096
	v_mfma_f32_32x32x16_bf16 v[80:95], v[132:135], v[136:139], v[80:95]
	v_mfma_f32_32x32x16_bf16 v[64:79], v[132:135], v[140:143], v[64:79]
	v_add_u32_e32 v165, v167, v188
	v_add_u32_e32 v164, v166, v188
	s_waitcnt lgkmcnt(0)
	v_mfma_f32_32x32x16_bf16 v[112:127], v[144:147], v[152:155], v[112:127]
	ds_read_b128 v[136:139], v165 offset:32768
	ds_read_b128 v[128:131], v164
	v_mfma_f32_32x32x16_bf16 v[96:111], v[144:147], v[156:159], v[96:111]
	ds_read_b128 v[140:143], v165 offset:36864
	ds_read_b128 v[132:135], v164 offset:4096
	v_mfma_f32_32x32x16_bf16 v[80:95], v[148:151], v[152:155], v[80:95]
	v_mfma_f32_32x32x16_bf16 v[64:79], v[148:151], v[156:159], v[64:79]
	v_add_u32_e32 v165, v167, v187
	v_add_u32_e32 v164, v166, v187
	s_waitcnt lgkmcnt(0)
	v_mfma_f32_32x32x16_bf16 v[112:127], v[128:131], v[136:139], v[112:127]
	ds_read_b128 v[152:155], v165 offset:32768
	ds_read_b128 v[144:147], v164
	v_mfma_f32_32x32x16_bf16 v[96:111], v[128:131], v[140:143], v[96:111]
	ds_read_b128 v[156:159], v165 offset:36864
	ds_read_b128 v[148:151], v164 offset:4096
	v_mfma_f32_32x32x16_bf16 v[80:95], v[132:135], v[136:139], v[80:95]
	v_mfma_f32_32x32x16_bf16 v[64:79], v[132:135], v[140:143], v[64:79]
	s_setprio 0
	s_waitcnt vmcnt(6) lgkmcnt(0)
	s_add_i32 s100, s42, 1
	s_cmp_lg_u32 s42, 2
	s_cselect_b32 s42, s100, 0
	s_add_u32 s48, s48, 0x80
	s_addc_u32 s49, s49, 0
	s_cmpk_lg_i32 s48, 0xf00
	s_barrier
	s_cbranch_scc1 .Ld2_loop
	v_mfma_f32_32x32x16_bf16 v[112:127], v[144:147], v[152:155], v[112:127]
	v_mfma_f32_32x32x16_bf16 v[96:111], v[144:147], v[156:159], v[96:111]
	v_mfma_f32_32x32x16_bf16 v[80:95], v[148:151], v[152:155], v[80:95]
	v_mfma_f32_32x32x16_bf16 v[64:79], v[148:151], v[156:159], v[64:79]

; DI void wait_vm0() { asm volatile("s_waitcnt vmcnt(0)" ::: "memory"); }
; DI void bar_() { __builtin_amdgcn_s_barrier(); }
; #define GLDS(gp, lp) __builtin_amdgcn_global_load_lds((const unsigned*)(gp), (__attribute__((address_space(3))) unsigned*)(lp), 16, 0, 0)
; #define SB_ __builtin_amdgcn_sched_barrier(0)
; #define LOADF(A_, B_, ks) do { const int po_ = (((ks) * 2 + hh) ^ sw) * 16; \
;       _Pragma("unroll") for (int tm = 0; tm < TM; ++tm) A_[tm] = *(const bf16x8*)(As + tm * 32 * LDR + po_); \
;       _Pragma("unroll") for (int tn = 0; tn < TN; ++tn) B_[tn] = *(const bf16x8*)(Bs + tn * 32 * LDR + po_); } while (0)
; template <int TM, int TN, int WM, int WN, bool SUMSQ, int NST, class AF, class BF, class AFN, class BFN>
; DI void gemm8x(f32x16 (&acc)[TM][TN], AF arow, BF brow, int K, char* smem, float& sumsq, bool pre, bool hasNext, AFN arowN, BFN browN) {
;     ...
;   auto compute = [&](const char* cur, char* nxt, bool issue, const bf16_t* q0, const bf16_t* q1, const bf16_t* q2, const bf16_t* q3,
;                      const bf16_t* s0, const bf16_t* s1, const bf16_t* s2, const bf16_t* s3) {
;     const char* As = cur + aoff;
;     const char* Bs = cur + boff;
;     char* l_ = nxt + t * 16; char* m_ = l_ + RA * LDR;
;     bf16x8 a0[TM], b0[TN], a1[TM], b1[TN];
;     ...
;     LOADF(a0, b0, 0);
;     LOADF(a1, b1, 1);
;     SB_;
;     if (issue) { if (a0v) GLDS(q0, l_); if (a1v) GLDS(q1, l_ + 8192); }
;     SB_;
;     __builtin_amdgcn_s_setprio(1);
;     MMF(a0, b0);
;     LOADF(a0, b0, 2);
;     SB_;
;     if (issue) { if (a2v) GLDS(q2, l_ + 16384); if (a3v) GLDS(q3, l_ + 24576); }
;     SB_;
;     MMF(a1, b1);
;     LOADF(a1, b1, 3);
;     SB_;
;     if (issue) { if (b0v) GLDS(s0, m_); if (b1v) GLDS(s1, m_ + 8192); }
;     SB_;
;     MMF(a0, b0);
;     SB_;
;     if (issue) { if (b2v) GLDS(s2, m_ + 16384); if (b3v) GLDS(s3, m_ + 24576); }
;     SB_;
;     MMF(a1, b1);
;     __builtin_amdgcn_s_setprio(0);
;     ...
;   for (int kt = 0; kt < nk - 1; ++kt) {
;     SB_;
;     if (NST == 2) {
;       const int ko = (kt + 1) * 64;
;       compute(smem + (kt & 1) * STAGE, smem + ((kt + 1) & 1) * STAGE, true, pa0 + ko, pa1 + ko, pa2 + ko, pa3 + ko, pb0 + ko, pb1 + ko, pb2 + ko, pb3 + ko);
;       SB_;
;       wait_vm0(); bar_();
.Lp6_loop:
	s_and_b32 s50, s24, 0x10000
	v_add_u32_e32 v225, s50, v211
	v_add_u32_e32 v224, s50, v208
	s_xor_b32 s50, s50, 0x10000
	s_add_i32 s50, s50, s51
	v_add_u32_e32 v226, v225, v207
	v_add_u32_e32 v227, v224, v207
	v_mfma_f32_32x32x16_bf16 v[112:127], v[148:151], v[140:143], v[112:127]
	ds_read_b128 v[164:167], v226 offset:32768
	ds_read_b128 v[172:175], v227
	s_mov_b32 m0, s50
	v_lshl_add_u64 v[228:229], v[186:187], 0, s[26:27]
	global_load_lds_dwordx4 v[228:229], off
	v_mfma_f32_32x32x16_bf16 v[48:63], v[148:151], v[132:135], v[48:63]
	ds_read_b128 v[156:159], v226 offset:36864
	ds_read_b128 v[168:171], v227 offset:4096
	s_add_u32 m0, s50, 0x2000
	v_lshl_add_u64 v[230:231], v[188:189], 0, s[26:27]
	global_load_lds_dwordx4 v[230:231], off
	v_mfma_f32_32x32x16_bf16 v[96:111], v[144:147], v[140:143], v[96:111]
	ds_read_b128 v[160:163], v227 offset:8192
	s_add_u32 m0, s50, 0x4000
	v_lshl_add_u64 v[228:229], v[190:191], 0, s[26:27]
	global_load_lds_dwordx4 v[228:229], off
	v_mfma_f32_32x32x16_bf16 v[32:47], v[144:147], v[132:135], v[32:47]
	ds_read_b128 v[152:155], v227 offset:12288
	s_add_u32 m0, s50, 0x6000
	v_lshl_add_u64 v[230:231], v[192:193], 0, s[26:27]
	global_load_lds_dwordx4 v[230:231], off
	v_mfma_f32_32x32x16_bf16 v[80:95], v[136:139], v[140:143], v[80:95]
	s_add_u32 m0, s50, 0x8000
	v_lshl_add_u64 v[228:229], v[194:195], 0, s[26:27]
	global_load_lds_dwordx4 v[228:229], off
	v_mfma_f32_32x32x16_bf16 v[16:31], v[136:139], v[132:135], v[16:31]
	s_add_u32 m0, s50, 0xa000
	v_lshl_add_u64 v[230:231], v[196:197], 0, s[26:27]
	global_load_lds_dwordx4 v[230:231], off
	v_mfma_f32_32x32x16_bf16 v[64:79], v[128:131], v[140:143], v[64:79]
	s_add_u32 m0, s50, 0xc000
	v_lshl_add_u64 v[228:229], v[198:199], 0, s[26:27]
	global_load_lds_dwordx4 v[228:229], off
	v_mfma_f32_32x32x16_bf16 v[0:15], v[128:131], v[132:135], v[0:15]
	s_add_u32 m0, s50, 0xe000
	v_lshl_add_u64 v[230:231], v[200:201], 0, s[26:27]
	global_load_lds_dwordx4 v[230:231], off
.Lp6_g0:
	v_add_u32_e32 v226, v225, v206
	v_add_u32_e32 v227, v224, v206
	s_waitcnt lgkmcnt(0)
	v_mfma_f32_32x32x16_bf16 v[112:127], v[172:175], v[164:167], v[112:127]
	ds_read_b128 v[140:143], v226 offset:32768
	ds_read_b128 v[148:151], v227
	v_mfma_f32_32x32x16_bf16 v[48:63], v[172:175], v[156:159], v[48:63]
	ds_read_b128 v[132:135], v226 offset:36864
	ds_read_b128 v[144:147], v227 offset:4096
	v_mfma_f32_32x32x16_bf16 v[96:111], v[168:171], v[164:167], v[96:111]
	ds_read_b128 v[136:139], v227 offset:8192
	v_mfma_f32_32x32x16_bf16 v[32:47], v[168:171], v[156:159], v[32:47]
	ds_read_b128 v[128:131], v227 offset:12288
	v_mfma_f32_32x32x16_bf16 v[80:95], v[160:163], v[164:167], v[80:95]
	v_mfma_f32_32x32x16_bf16 v[16:31], v[160:163], v[156:159], v[16:31]
	v_mfma_f32_32x32x16_bf16 v[64:79], v[152:155], v[164:167], v[64:79]
	v_mfma_f32_32x32x16_bf16 v[0:15], v[152:155], v[156:159], v[0:15]
	v_add_u32_e32 v226, v225, v205
	v_add_u32_e32 v227, v224, v205
	s_waitcnt lgkmcnt(0)
	v_mfma_f32_32x32x16_bf16 v[112:127], v[148:151], v[140:143], v[112:127]
	ds_read_b128 v[164:167], v226 offset:32768
	ds_read_b128 v[172:175], v227
	v_mfma_f32_32x32x16_bf16 v[48:63], v[148:151], v[132:135], v[48:63]
	ds_read_b128 v[156:159], v226 offset:36864
	ds_read_b128 v[168:171], v227 offset:4096
	v_mfma_f32_32x32x16_bf16 v[96:111], v[144:147], v[140:143], v[96:111]
	ds_read_b128 v[160:163], v227 offset:8192
	v_mfma_f32_32x32x16_bf16 v[32:47], v[144:147], v[132:135], v[32:47]
	ds_read_b128 v[152:155], v227 offset:12288
	v_mfma_f32_32x32x16_bf16 v[80:95], v[136:139], v[140:143], v[80:95]
	v_mfma_f32_32x32x16_bf16 v[16:31], v[136:139], v[132:135], v[16:31]
	v_mfma_f32_32x32x16_bf16 v[64:79], v[128:131], v[140:143], v[64:79]
	v_mfma_f32_32x32x16_bf16 v[0:15], v[128:131], v[132:135], v[0:15]
	v_add_u32_e32 v226, v225, v204
	v_add_u32_e32 v227, v224, v204
	s_waitcnt lgkmcnt(0)
	v_mfma_f32_32x32x16_bf16 v[112:127], v[172:175], v[164:167], v[112:127]
	ds_read_b128 v[140:143], v226 offset:32768
	ds_read_b128 v[148:151], v227
	v_mfma_f32_32x32x16_bf16 v[48:63], v[172:175], v[156:159], v[48:63]
	ds_read_b128 v[132:135], v226 offset:36864
	ds_read_b128 v[144:147], v227 offset:4096
	v_mfma_f32_32x32x16_bf16 v[96:111], v[168:171], v[164:167], v[96:111]
	ds_read_b128 v[136:139], v227 offset:8192
	v_mfma_f32_32x32x16_bf16 v[32:47], v[168:171], v[156:159], v[32:47]
	ds_read_b128 v[128:131], v227 offset:12288
	v_mfma_f32_32x32x16_bf16 v[80:95], v[160:163], v[164:167], v[80:95]
	v_mfma_f32_32x32x16_bf16 v[16:31], v[160:163], v[156:159], v[16:31]
	v_mfma_f32_32x32x16_bf16 v[64:79], v[152:155], v[164:167], v[64:79]
	v_mfma_f32_32x32x16_bf16 v[0:15], v[152:155], v[156:159], v[0:15]
	s_setprio 0
	s_waitcnt vmcnt(0) lgkmcnt(0)
	s_add_i32 s24, s24, 0x10000
	s_add_u32 s26, s26, 0x80
	s_addc_u32 s27, s27, 0
	s_cmpk_eq_i32 s26, 0x780
	s_barrier
; DI void lds_sync() { wait_lgkm0(); bar_(); }
; #define GLDS(gp, lp) __builtin_amdgcn_global_load_lds((const unsigned*)(gp), (__attribute__((address_space(3))) unsigned*)(lp), 16, 0, 0)
; #define SB_ __builtin_amdgcn_sched_barrier(0)
; template <int TM, int TN, int WM, int WN, bool SUMSQ, int NST, class AF, class BF, class AFN, class BFN>
; DI void gemm8x(f32x16 (&acc)[TM][TN], AF arow, BF brow, int K, char* smem, float& sumsq, bool pre, bool hasNext, AFN arowN, BFN browN) {
;     ...
;   auto compute = [&](const char* cur, char* nxt, bool issue, const bf16_t* q0, const bf16_t* q1, const bf16_t* q2, const bf16_t* q3,
;                      const bf16_t* s0, const bf16_t* s1, const bf16_t* s2, const bf16_t* s3) {
;     const char* As = cur + aoff;
;     const char* Bs = cur + boff;
;     char* l_ = nxt + t * 16; char* m_ = l_ + RA * LDR;
;     bf16x8 a0[TM], b0[TN], a1[TM], b1[TN];
;     ...
;     LOADF(a0, b0, 0);
;     LOADF(a1, b1, 1);
;     SB_;
;     if (issue) { if (a0v) GLDS(q0, l_); if (a1v) GLDS(q1, l_ + 8192); }
;     SB_;
;     __builtin_amdgcn_s_setprio(1);
;     MMF(a0, b0);
;     LOADF(a0, b0, 2);
;     SB_;
;     if (issue) { if (a2v) GLDS(q2, l_ + 16384); if (a3v) GLDS(q3, l_ + 24576); }
;     SB_;
;     MMF(a1, b1);
;     LOADF(a1, b1, 3);
;     SB_;
;     if (issue) { if (b0v) GLDS(s0, m_); if (b1v) GLDS(s1, m_ + 8192); }
;     SB_;
;     MMF(a0, b0);
;     SB_;
;     if (issue) { if (b2v) GLDS(s2, m_ + 16384); if (b3v) GLDS(s3, m_ + 24576); }
;     SB_;
;     MMF(a1, b1);
;     __builtin_amdgcn_s_setprio(0);
;     ...
;     const bf16_t *q0 = pa0, *q1 = pa0, *q2 = pa0, *q3 = pa0, *s0 = pa0, *s1 = pa0, *s2 = pa0, *s3 = pa0;
;     if (hasNext) {
;       q0 = arowN(a0v ? row0 : 0) + c * 8; q1 = arowN(a1v ? row0 + 64 : 0) + c * 8; q2 = arowN(a2v ? row0 + 128 : 0) + c * 8; q3 = arowN(a3v ? row0 + 192 : 0) + c * 8;
;       s0 = browN(b0v ? row0 : 0) + c * 8; s1 = browN(b1v ? row0 + 64 : 0) + c * 8; s2 = browN(b2v ? row0 + 128 : 0) + c * 8; s3 = browN(b3v ? row0 + 192 : 0) + c * 8;
;     }
;     SB_;
;     compute(smem + ((nk - 1) & 1) * STAGE, smem, hasNext, q0, q1, q2, q3, s0, s1, s2, s3);
;     SB_;
;     lds_sync();
	s_cbranch_scc0 .Lp6_loop
	s_and_b32 s50, s24, 0x10000
	v_add_u32_e32 v225, s50, v211
	v_add_u32_e32 v224, s50, v208
	s_xor_b32 s50, s50, 0x10000
	s_add_i32 s50, s50, s51
	v_add_u32_e32 v226, v225, v207
	v_add_u32_e32 v227, v224, v207
	v_mfma_f32_32x32x16_bf16 v[112:127], v[148:151], v[140:143], v[112:127]
	ds_read_b128 v[164:167], v226 offset:32768
	ds_read_b128 v[172:175], v227
	v_mfma_f32_32x32x16_bf16 v[48:63], v[148:151], v[132:135], v[48:63]
	ds_read_b128 v[156:159], v226 offset:36864
	ds_read_b128 v[168:171], v227 offset:4096
	v_mfma_f32_32x32x16_bf16 v[96:111], v[144:147], v[140:143], v[96:111]
	ds_read_b128 v[160:163], v227 offset:8192
	v_mfma_f32_32x32x16_bf16 v[32:47], v[144:147], v[132:135], v[32:47]
	ds_read_b128 v[152:155], v227 offset:12288
	v_mfma_f32_32x32x16_bf16 v[80:95], v[136:139], v[140:143], v[80:95]
	v_mfma_f32_32x32x16_bf16 v[16:31], v[136:139], v[132:135], v[16:31]
	v_mfma_f32_32x32x16_bf16 v[64:79], v[128:131], v[140:143], v[64:79]
	v_mfma_f32_32x32x16_bf16 v[0:15], v[128:131], v[132:135], v[0:15]
	v_add_u32_e32 v226, v225, v206
	v_add_u32_e32 v227, v224, v206
	s_waitcnt lgkmcnt(0)
	v_mfma_f32_32x32x16_bf16 v[112:127], v[172:175], v[164:167], v[112:127]
	ds_read_b128 v[140:143], v226 offset:32768
	ds_read_b128 v[148:151], v227
	v_mfma_f32_32x32x16_bf16 v[48:63], v[172:175], v[156:159], v[48:63]
	ds_read_b128 v[132:135], v226 offset:36864
	ds_read_b128 v[144:147], v227 offset:4096
	v_mfma_f32_32x32x16_bf16 v[96:111], v[168:171], v[164:167], v[96:111]
	ds_read_b128 v[136:139], v227 offset:8192
	v_mfma_f32_32x32x16_bf16 v[32:47], v[168:171], v[156:159], v[32:47]
	ds_read_b128 v[128:131], v227 offset:12288
	v_mfma_f32_32x32x16_bf16 v[80:95], v[160:163], v[164:167], v[80:95]
	v_mfma_f32_32x32x16_bf16 v[16:31], v[160:163], v[156:159], v[16:31]
	v_mfma_f32_32x32x16_bf16 v[64:79], v[152:155], v[164:167], v[64:79]
	v_mfma_f32_32x32x16_bf16 v[0:15], v[152:155], v[156:159], v[0:15]
	v_add_u32_e32 v226, v225, v205
	v_add_u32_e32 v227, v224, v205
	s_waitcnt lgkmcnt(0)
	v_mfma_f32_32x32x16_bf16 v[112:127], v[148:151], v[140:143], v[112:127]
	ds_read_b128 v[164:167], v226 offset:32768
	ds_read_b128 v[172:175], v227
	v_mfma_f32_32x32x16_bf16 v[48:63], v[148:151], v[132:135], v[48:63]
	ds_read_b128 v[156:159], v226 offset:36864
	ds_read_b128 v[168:171], v227 offset:4096
	v_mfma_f32_32x32x16_bf16 v[96:111], v[144:147], v[140:143], v[96:111]
	ds_read_b128 v[160:163], v227 offset:8192
	v_mfma_f32_32x32x16_bf16 v[32:47], v[144:147], v[132:135], v[32:47]
	ds_read_b128 v[152:155], v227 offset:12288
	v_mfma_f32_32x32x16_bf16 v[80:95], v[136:139], v[140:143], v[80:95]
	v_mfma_f32_32x32x16_bf16 v[16:31], v[136:139], v[132:135], v[16:31]
	v_mfma_f32_32x32x16_bf16 v[64:79], v[128:131], v[140:143], v[64:79]
	v_mfma_f32_32x32x16_bf16 v[0:15], v[128:131], v[132:135], v[0:15]
	v_add_u32_e32 v226, v225, v204
	v_add_u32_e32 v227, v224, v204
	s_waitcnt lgkmcnt(0)
	v_mfma_f32_32x32x16_bf16 v[112:127], v[172:175], v[164:167], v[112:127]
	ds_read_b128 v[140:143], v226 offset:32768
	ds_read_b128 v[148:151], v227
	v_mfma_f32_32x32x16_bf16 v[48:63], v[172:175], v[156:159], v[48:63]
	ds_read_b128 v[132:135], v226 offset:36864
	ds_read_b128 v[144:147], v227 offset:4096
	v_mfma_f32_32x32x16_bf16 v[96:111], v[168:171], v[164:167], v[96:111]
	ds_read_b128 v[136:139], v227 offset:8192
	v_mfma_f32_32x32x16_bf16 v[32:47], v[168:171], v[156:159], v[32:47]
	ds_read_b128 v[128:131], v227 offset:12288
	v_mfma_f32_32x32x16_bf16 v[80:95], v[160:163], v[164:167], v[80:95]
	v_mfma_f32_32x32x16_bf16 v[16:31], v[160:163], v[156:159], v[16:31]
	v_mfma_f32_32x32x16_bf16 v[64:79], v[152:155], v[164:167], v[64:79]
	v_mfma_f32_32x32x16_bf16 v[0:15], v[152:155], v[156:159], v[0:15]
	s_waitcnt lgkmcnt(0)
	v_mfma_f32_32x32x16_bf16 v[112:127], v[148:151], v[140:143], v[112:127]
	v_mfma_f32_32x32x16_bf16 v[48:63], v[148:151], v[132:135], v[48:63]
	v_mfma_f32_32x32x16_bf16 v[96:111], v[144:147], v[140:143], v[96:111]
	v_mfma_f32_32x32x16_bf16 v[32:47], v[144:147], v[132:135], v[32:47]
	v_mfma_f32_32x32x16_bf16 v[80:95], v[136:139], v[140:143], v[80:95]
	v_mfma_f32_32x32x16_bf16 v[16:31], v[136:139], v[132:135], v[16:31]
	v_mfma_f32_32x32x16_bf16 v[64:79], v[128:131], v[140:143], v[64:79]
	v_mfma_f32_32x32x16_bf16 v[0:15], v[128:131], v[132:135], v[0:15]
	s_lshl_b32 s6, s45, 18
	s_branch .Lp6_cont

; DI void wait_vm0() { asm volatile("s_waitcnt vmcnt(0)" ::: "memory"); }
; DI void bar_() { __builtin_amdgcn_s_barrier(); }
; #define SB_ __builtin_amdgcn_sched_barrier(0)
; template <int TM, int TN, int WM, int WN, bool SUMSQ, int NST, class AF, class BF, class AFN, class BFN>
; DI void gemm8x(f32x16 (&acc)[TM][TN], AF arow, BF brow, int K, char* smem, float& sumsq, bool pre, bool hasNext, AFN arowN, BFN browN) {
;     ...
;   for (int kt = 0; kt < nk - 1; ++kt) {
;     SB_;
;     if (NST == 2) {
;       const int ko = (kt + 1) * 64;
;       compute(smem + (kt & 1) * STAGE, smem + ((kt + 1) & 1) * STAGE, true, pa0 + ko, pa1 + ko, pa2 + ko, pa3 + ko, pb0 + ko, pb1 + ko, pb2 + ko, pb3 + ko);
;       SB_;
;       wait_vm0(); bar_();
; DI void phase9_10(const Params& p, char* smem) {
;     ...
;       gemm8x<4, 2, 2, 4, false, 2>(acc, [&](int row) { return Ab + (size_t)row * DM; }, [&](int row) { return hb + (size_t)ib[row] * DM; }, DM, smem, dummy,
;                                    pre, hasNext, [&](int row) { return AbN + (size_t)row * DM; }, [&](int row) { return hb + (size_t)ib[row] * DM; });
.Lp9_loop:
	s_and_b32 s81, s80, 0x10000
	v_add_u32_e32 v237, s81, v231
	v_add_u32_e32 v236, s81, v228
	s_xor_b32 s81, s81, 0x10000
	s_add_i32 s81, s81, s82
	v_add_u32_e32 v238, v237, v227
	v_add_u32_e32 v239, v236, v227
	v_mfma_f32_32x32x16_bf16 v[112:127], v[148:151], v[140:143], v[112:127]
	ds_read_b128 v[164:167], v238 offset:32768
	ds_read_b128 v[172:175], v239
	s_mov_b32 m0, s81
	v_lshl_add_u64 v[240:241], v[204:205], 0, s[52:53]
	global_load_lds_dwordx4 v[240:241], off
	v_mfma_f32_32x32x16_bf16 v[48:63], v[148:151], v[132:135], v[48:63]
	ds_read_b128 v[156:159], v238 offset:36864
	ds_read_b128 v[168:171], v239 offset:4096
	s_add_u32 m0, s81, 0x2000
	v_lshl_add_u64 v[242:243], v[206:207], 0, s[52:53]
	global_load_lds_dwordx4 v[242:243], off
	v_mfma_f32_32x32x16_bf16 v[96:111], v[144:147], v[140:143], v[96:111]
	ds_read_b128 v[160:163], v239 offset:8192
	s_add_u32 m0, s81, 0x4000
	v_lshl_add_u64 v[240:241], v[208:209], 0, s[52:53]
	global_load_lds_dwordx4 v[240:241], off
	v_mfma_f32_32x32x16_bf16 v[32:47], v[144:147], v[132:135], v[32:47]
	ds_read_b128 v[152:155], v239 offset:12288
	s_add_u32 m0, s81, 0x6000
	v_lshl_add_u64 v[242:243], v[210:211], 0, s[52:53]
	global_load_lds_dwordx4 v[242:243], off
	v_mfma_f32_32x32x16_bf16 v[80:95], v[136:139], v[140:143], v[80:95]
	s_add_u32 m0, s81, 0x8000
	v_lshl_add_u64 v[240:241], v[212:213], 0, s[52:53]
	global_load_lds_dwordx4 v[240:241], off
	v_mfma_f32_32x32x16_bf16 v[16:31], v[136:139], v[132:135], v[16:31]
	s_add_u32 m0, s81, 0xa000
	v_lshl_add_u64 v[242:243], v[214:215], 0, s[52:53]
	global_load_lds_dwordx4 v[242:243], off
	v_mfma_f32_32x32x16_bf16 v[64:79], v[128:131], v[140:143], v[64:79]
	s_add_u32 m0, s81, 0xc000
	v_lshl_add_u64 v[240:241], v[216:217], 0, s[52:53]
	global_load_lds_dwordx4 v[240:241], off
	v_mfma_f32_32x32x16_bf16 v[0:15], v[128:131], v[132:135], v[0:15]
	s_add_u32 m0, s81, 0xe000
	v_lshl_add_u64 v[242:243], v[218:219], 0, s[52:53]
	global_load_lds_dwordx4 v[242:243], off
.Lp9_g0:
	v_add_u32_e32 v238, v237, v226
	v_add_u32_e32 v239, v236, v226
	s_waitcnt lgkmcnt(0)
	v_mfma_f32_32x32x16_bf16 v[112:127], v[172:175], v[164:167], v[112:127]
	ds_read_b128 v[140:143], v238 offset:32768
	ds_read_b128 v[148:151], v239
	v_mfma_f32_32x32x16_bf16 v[48:63], v[172:175], v[156:159], v[48:63]
	ds_read_b128 v[132:135], v238 offset:36864
	ds_read_b128 v[144:147], v239 offset:4096
	v_mfma_f32_32x32x16_bf16 v[96:111], v[168:171], v[164:167], v[96:111]
	ds_read_b128 v[136:139], v239 offset:8192
	v_mfma_f32_32x32x16_bf16 v[32:47], v[168:171], v[156:159], v[32:47]
	ds_read_b128 v[128:131], v239 offset:12288
	v_mfma_f32_32x32x16_bf16 v[80:95], v[160:163], v[164:167], v[80:95]
	v_mfma_f32_32x32x16_bf16 v[16:31], v[160:163], v[156:159], v[16:31]
	v_mfma_f32_32x32x16_bf16 v[64:79], v[152:155], v[164:167], v[64:79]
	v_mfma_f32_32x32x16_bf16 v[0:15], v[152:155], v[156:159], v[0:15]
	v_add_u32_e32 v238, v237, v225
	v_add_u32_e32 v239, v236, v225
	s_waitcnt lgkmcnt(0)
	v_mfma_f32_32x32x16_bf16 v[112:127], v[148:151], v[140:143], v[112:127]
	ds_read_b128 v[164:167], v238 offset:32768
	ds_read_b128 v[172:175], v239
	v_mfma_f32_32x32x16_bf16 v[48:63], v[148:151], v[132:135], v[48:63]
	ds_read_b128 v[156:159], v238 offset:36864
	ds_read_b128 v[168:171], v239 offset:4096
	v_mfma_f32_32x32x16_bf16 v[96:111], v[144:147], v[140:143], v[96:111]
	ds_read_b128 v[160:163], v239 offset:8192
	v_mfma_f32_32x32x16_bf16 v[32:47], v[144:147], v[132:135], v[32:47]
	ds_read_b128 v[152:155], v239 offset:12288
	v_mfma_f32_32x32x16_bf16 v[80:95], v[136:139], v[140:143], v[80:95]
	v_mfma_f32_32x32x16_bf16 v[16:31], v[136:139], v[132:135], v[16:31]
	v_mfma_f32_32x32x16_bf16 v[64:79], v[128:131], v[140:143], v[64:79]
	v_mfma_f32_32x32x16_bf16 v[0:15], v[128:131], v[132:135], v[0:15]
	v_add_u32_e32 v238, v237, v224
	v_add_u32_e32 v239, v236, v224
	s_waitcnt lgkmcnt(0)
	v_mfma_f32_32x32x16_bf16 v[112:127], v[172:175], v[164:167], v[112:127]
	ds_read_b128 v[140:143], v238 offset:32768
	ds_read_b128 v[148:151], v239
	v_mfma_f32_32x32x16_bf16 v[48:63], v[172:175], v[156:159], v[48:63]
	ds_read_b128 v[132:135], v238 offset:36864
	ds_read_b128 v[144:147], v239 offset:4096
	v_mfma_f32_32x32x16_bf16 v[96:111], v[168:171], v[164:167], v[96:111]
	ds_read_b128 v[136:139], v239 offset:8192
	v_mfma_f32_32x32x16_bf16 v[32:47], v[168:171], v[156:159], v[32:47]
	ds_read_b128 v[128:131], v239 offset:12288
	v_mfma_f32_32x32x16_bf16 v[80:95], v[160:163], v[164:167], v[80:95]
	v_mfma_f32_32x32x16_bf16 v[16:31], v[160:163], v[156:159], v[16:31]
	v_mfma_f32_32x32x16_bf16 v[64:79], v[152:155], v[164:167], v[64:79]
	v_mfma_f32_32x32x16_bf16 v[0:15], v[152:155], v[156:159], v[0:15]
	s_setprio 0
	s_waitcnt vmcnt(0) lgkmcnt(0)
	s_add_i32 s80, s80, 0x10000
	s_add_u32 s52, s52, 0x80
	s_addc_u32 s53, s53, 0
	s_cmpk_eq_i32 s52, 0x780
	s_barrier
	s_cbranch_scc0 .Lp9_loop
; #define SB_ __builtin_amdgcn_sched_barrier(0)
; template <int TM, int TN, int WM, int WN, bool SUMSQ, int NST, class AF, class BF, class AFN, class BFN>
; DI void gemm8x(f32x16 (&acc)[TM][TN], AF arow, BF brow, int K, char* smem, float& sumsq, bool pre, bool hasNext, AFN arowN, BFN browN) {
;     ...
;     const bf16_t *q0 = pa0, *q1 = pa0, *q2 = pa0, *q3 = pa0, *s0 = pa0, *s1 = pa0, *s2 = pa0, *s3 = pa0;
;     if (hasNext) {
;       q0 = arowN(a0v ? row0 : 0) + c * 8; q1 = arowN(a1v ? row0 + 64 : 0) + c * 8; q2 = arowN(a2v ? row0 + 128 : 0) + c * 8; q3 = arowN(a3v ? row0 + 192 : 0) + c * 8;
;       s0 = browN(b0v ? row0 : 0) + c * 8; s1 = browN(b1v ? row0 + 64 : 0) + c * 8; s2 = browN(b2v ? row0 + 128 : 0) + c * 8; s3 = browN(b3v ? row0 + 192 : 0) + c * 8;
;     }
;     SB_;
;     compute(smem + ((nk - 1) & 1) * STAGE, smem, hasNext, q0, q1, q2, q3, s0, s1, s2, s3);
; DI void phase9_10(const Params& p, char* smem) {
;     ...
;     for (int ft = 0; ft < 4; ++ft) {
;       const bool hasNext = ft < 3;
;       const bf16_t* Ab = p.WguT + ((size_t)e * 1024 + ft * 256) * DM;
;       const bf16_t* AbN = Ab + (size_t)256 * DM;
;       f32x16 acc[4][2];
; #pragma unroll
;       for (int a = 0; a < 4; ++a)
; #pragma unroll
;         for (int c = 0; c < 2; ++c) acc[a][c] = zero16();
;       float dummy = 0.f;
;       gemm8x<4, 2, 2, 4, false, 2>(acc, [&](int row) { return Ab + (size_t)row * DM; }, [&](int row) { return hb + (size_t)ib[row] * DM; }, DM, smem, dummy,
;                                    pre, hasNext, [&](int row) { return AbN + (size_t)row * DM; }, [&](int row) { return hb + (size_t)ib[row] * DM; });
;       pre = hasNext;
	s_and_b32 s81, s80, 0x10000
	v_add_u32_e32 v237, s81, v231
	v_add_u32_e32 v236, s81, v228
	s_xor_b32 s81, s81, 0x10000
	s_add_i32 s81, s81, s82
	v_add_u32_e32 v238, v237, v227
	v_add_u32_e32 v239, v236, v227
	v_mfma_f32_32x32x16_bf16 v[112:127], v[148:151], v[140:143], v[112:127]
	ds_read_b128 v[164:167], v238 offset:32768
	ds_read_b128 v[172:175], v239
	v_mfma_f32_32x32x16_bf16 v[48:63], v[148:151], v[132:135], v[48:63]
	ds_read_b128 v[156:159], v238 offset:36864
	ds_read_b128 v[168:171], v239 offset:4096
	v_mfma_f32_32x32x16_bf16 v[96:111], v[144:147], v[140:143], v[96:111]
	ds_read_b128 v[160:163], v239 offset:8192
	v_mfma_f32_32x32x16_bf16 v[32:47], v[144:147], v[132:135], v[32:47]
	ds_read_b128 v[152:155], v239 offset:12288
	v_mfma_f32_32x32x16_bf16 v[80:95], v[136:139], v[140:143], v[80:95]
	v_mfma_f32_32x32x16_bf16 v[16:31], v[136:139], v[132:135], v[16:31]
	v_mfma_f32_32x32x16_bf16 v[64:79], v[128:131], v[140:143], v[64:79]
	v_mfma_f32_32x32x16_bf16 v[0:15], v[128:131], v[132:135], v[0:15]
	v_add_u32_e32 v238, v237, v226
	v_add_u32_e32 v239, v236, v226
	s_waitcnt lgkmcnt(0)
	v_mfma_f32_32x32x16_bf16 v[112:127], v[172:175], v[164:167], v[112:127]
	ds_read_b128 v[140:143], v238 offset:32768
	ds_read_b128 v[148:151], v239
	v_mfma_f32_32x32x16_bf16 v[48:63], v[172:175], v[156:159], v[48:63]
	ds_read_b128 v[132:135], v238 offset:36864
	ds_read_b128 v[144:147], v239 offset:4096
	v_mfma_f32_32x32x16_bf16 v[96:111], v[168:171], v[164:167], v[96:111]
	ds_read_b128 v[136:139], v239 offset:8192
	v_mfma_f32_32x32x16_bf16 v[32:47], v[168:171], v[156:159], v[32:47]
	ds_read_b128 v[128:131], v239 offset:12288
	v_mfma_f32_32x32x16_bf16 v[80:95], v[160:163], v[164:167], v[80:95]
	v_mfma_f32_32x32x16_bf16 v[16:31], v[160:163], v[156:159], v[16:31]
	v_mfma_f32_32x32x16_bf16 v[64:79], v[152:155], v[164:167], v[64:79]
	v_mfma_f32_32x32x16_bf16 v[0:15], v[152:155], v[156:159], v[0:15]
	v_add_u32_e32 v238, v237, v225
	v_add_u32_e32 v239, v236, v225
	s_waitcnt lgkmcnt(0)
	v_mfma_f32_32x32x16_bf16 v[112:127], v[148:151], v[140:143], v[112:127]
	ds_read_b128 v[164:167], v238 offset:32768
	ds_read_b128 v[172:175], v239
	v_mfma_f32_32x32x16_bf16 v[48:63], v[148:151], v[132:135], v[48:63]
	ds_read_b128 v[156:159], v238 offset:36864
	ds_read_b128 v[168:171], v239 offset:4096
	v_mfma_f32_32x32x16_bf16 v[96:111], v[144:147], v[140:143], v[96:111]
	ds_read_b128 v[160:163], v239 offset:8192
	v_mfma_f32_32x32x16_bf16 v[32:47], v[144:147], v[132:135], v[32:47]
	ds_read_b128 v[152:155], v239 offset:12288
	v_mfma_f32_32x32x16_bf16 v[80:95], v[136:139], v[140:143], v[80:95]
	v_mfma_f32_32x32x16_bf16 v[16:31], v[136:139], v[132:135], v[16:31]
	v_mfma_f32_32x32x16_bf16 v[64:79], v[128:131], v[140:143], v[64:79]
	v_mfma_f32_32x32x16_bf16 v[0:15], v[128:131], v[132:135], v[0:15]
	v_add_u32_e32 v238, v237, v224
	v_add_u32_e32 v239, v236, v224
	s_waitcnt lgkmcnt(0)
	v_mfma_f32_32x32x16_bf16 v[112:127], v[172:175], v[164:167], v[112:127]
	ds_read_b128 v[140:143], v238 offset:32768
	ds_read_b128 v[148:151], v239
	v_mfma_f32_32x32x16_bf16 v[48:63], v[172:175], v[156:159], v[48:63]
	ds_read_b128 v[132:135], v238 offset:36864
	ds_read_b128 v[144:147], v239 offset:4096
	v_mfma_f32_32x32x16_bf16 v[96:111], v[168:171], v[164:167], v[96:111]
	ds_read_b128 v[136:139], v239 offset:8192
	v_mfma_f32_32x32x16_bf16 v[32:47], v[168:171], v[156:159], v[32:47]
	ds_read_b128 v[128:131], v239 offset:12288
	v_mfma_f32_32x32x16_bf16 v[80:95], v[160:163], v[164:167], v[80:95]
	v_mfma_f32_32x32x16_bf16 v[16:31], v[160:163], v[156:159], v[16:31]
	v_mfma_f32_32x32x16_bf16 v[64:79], v[152:155], v[164:167], v[64:79]
	v_mfma_f32_32x32x16_bf16 v[0:15], v[152:155], v[156:159], v[0:15]
	s_waitcnt lgkmcnt(0)
	v_mfma_f32_32x32x16_bf16 v[112:127], v[148:151], v[140:143], v[112:127]
	v_mfma_f32_32x32x16_bf16 v[48:63], v[148:151], v[132:135], v[48:63]
	v_mfma_f32_32x32x16_bf16 v[96:111], v[144:147], v[140:143], v[96:111]
	v_mfma_f32_32x32x16_bf16 v[32:47], v[144:147], v[132:135], v[32:47]
	v_mfma_f32_32x32x16_bf16 v[80:95], v[136:139], v[140:143], v[80:95]
	v_mfma_f32_32x32x16_bf16 v[16:31], v[136:139], v[132:135], v[16:31]
	v_mfma_f32_32x32x16_bf16 v[64:79], v[128:131], v[140:143], v[64:79]
	v_mfma_f32_32x32x16_bf16 v[0:15], v[128:131], v[132:135], v[0:15]
	s_cmp_lg_u32 s79, 3
	s_cselect_b64 s[52:53], -1, 0
	s_cbranch_scc0 .Lp9_nonext
	global_load_dword v128, v[194:195], off
	global_load_dword v130, v[192:193], off
	global_load_dword v132, v[190:191], off
	global_load_dword v134, v[188:189], off
	s_add_u32 s12, s12, 0x80000
	s_addc_u32 s13, s13, 0
	v_lshl_add_u64 v[136:137], s[12:13], 0, v[196:197]
	v_lshl_add_u64 v[138:139], s[12:13], 0, v[198:199]
	v_lshl_add_u64 v[140:141], s[12:13], 0, v[200:201]
	v_lshl_add_u64 v[142:143], s[12:13], 0, v[202:203]
	v_lshl_add_u64 v[186:187], v[136:137], 0, v[184:185]
	v_lshl_add_u64 v[164:165], v[138:139], 0, v[184:185]
	v_lshl_add_u64 v[214:215], v[140:141], 0, v[184:185]
	v_lshl_add_u64 v[212:213], v[142:143], 0, v[184:185]
	s_waitcnt vmcnt(0)
	v_ashrrev_i32_e32 v129, 31, v128
	v_ashrrev_i32_e32 v131, 31, v130
	v_ashrrev_i32_e32 v133, 31, v132
	v_ashrrev_i32_e32 v135, 31, v134
	v_lshlrev_b64 v[128:129], 11, v[128:129]
	v_lshlrev_b64 v[130:131], 11, v[130:131]
	v_lshlrev_b64 v[132:133], 11, v[132:133]
	v_lshlrev_b64 v[134:135], 11, v[134:135]
	v_lshl_add_u64 v[128:129], s[48:49], 0, v[128:129]
	v_lshl_add_u64 v[130:131], s[48:49], 0, v[130:131]
	v_lshl_add_u64 v[132:133], s[48:49], 0, v[132:133]
	v_lshl_add_u64 v[134:135], s[48:49], 0, v[134:135]
	v_lshl_add_u64 v[210:211], v[128:129], 0, v[184:185]
	v_lshl_add_u64 v[208:209], v[130:131], 0, v[184:185]
	v_lshl_add_u64 v[206:207], v[132:133], 0, v[184:185]
	v_lshl_add_u64 v[204:205], v[134:135], 0, v[184:185]
	s_mov_b32 m0, s82
	s_nop 0
	global_load_lds_dwordx4 v[186:187], off
	s_add_u32 m0, s82, 0x2000
	s_nop 0
	global_load_lds_dwordx4 v[164:165], off
	s_add_u32 m0, s82, 0x4000
	s_nop 0
	global_load_lds_dwordx4 v[214:215], off
	s_add_u32 m0, s82, 0x6000
	s_nop 0
	global_load_lds_dwordx4 v[212:213], off
	s_add_u32 m0, s82, 0x8000
	s_nop 0
	global_load_lds_dwordx4 v[210:211], off
	s_add_u32 m0, s82, 0xa000
	s_nop 0
	global_load_lds_dwordx4 v[208:209], off
	s_add_u32 m0, s82, 0xc000
	s_nop 0
	global_load_lds_dwordx4 v[206:207], off
	s_add_u32 m0, s82, 0xe000
	s_nop 0
	global_load_lds_dwordx4 v[204:205], off
